# P3: first two counted waits after a unit epilogue with >=16 stores leave those stores outstanding (vmcnt 24); flag cleared for the 16-column forget-gate tile
# speedup vs baseline: 1.0011x; 1.0011x over previous
; #define PG8_STAGE(bufoff, gbase, voff) do { _Pragma("unroll") for (int _i = 0; _i < 2; ++_i) \
;         __builtin_amdgcn_global_load_lds((const unsigned*)((const char*)(gbase) + (voff)[_i]), (LAS unsigned*)(lds + (bufoff) + ldsw + _i * 8192), 16, 0, 0); } while (0)
; #define PG8_WAIT_V(n) asm volatile("s_waitcnt vmcnt(" #n ")" ::: "memory")
; #define PG8_BAR __builtin_amdgcn_s_barrier()
; template <class Epi>
; __device__ __forceinline__ void gemm_phase(LAS unsigned char* lds, const Gemm g, const Sched& S, const Epi& E) {
;     const int tid = threadIdx.x, wid = __builtin_amdgcn_readfirstlane(tid >> 6), lane = tid & 63, wr = wid >> 2, wc = wid & 3, fr = lane & 15, fq = lane >> 4;
;     const int K = g.K, nt = K / BK;
;     unsigned voffA[2], voffB[2];
; #pragma unroll
;     for (int i = 0; i < 2; ++i) { int R, C; stage_rc(tid * 16 + i * 8192, R, C); const int Rb = (R & ~31) + perm32(R & 31);
;         voffA[i] = (unsigned)(R * g.lda + C) * 2u; voffB[i] = (unsigned)(Rb * g.ldb + C) * 2u; }
;     const size_t kstep = (size_t)(BK * 2);
;     const size_t hstepA = (size_t)HALF * g.lda * 2, hstepB = (size_t)HALF * g.ldb * 2;
;     const size_t tstepA = 2 * hstepA, tstepB = 2 * hstepB;
;     const unsigned ldsw = (unsigned)wid * 1024u;
;     const int aoff = lds_byte(wr * 64 + fr, fq * 8), boff = lds_byte(wc * 32 + fr, fq * 8);
;     ...
;     Unit cur, nxt; int ui = 0;
;     if (!S.next(0, cur)) return;
;     Acc acc;
; #pragma unroll
;     for (int a = 0; a < 2; ++a)
; #pragma unroll
;         for (int b = 0; b < 2; ++b)
; #pragma unroll
;             for (int m = 0; m < 4; ++m)
; #pragma unroll
;                 for (int n = 0; n < 2; ++n) acc[a][b][m][n] = (f32x4){0.f, 0.f, 0.f, 0.f};
;     bf16x8 At[4][2], B0[2][2], B1[2][2];
;     const char* cA = (const char*)g.A + (size_t)cur.pm * tstepA + (size_t)cur.part * g.koff * 2; const char* cB = (const char*)g.Bt + (size_t)cur.pn * tstepB + (size_t)cur.part * g.koff * 2;
;     PG8_STAGE(PG8_SB(0, 0), cB, voffB); PG8_STAGE(PG8_SB(0, 1), cB + hstepB, voffB); PG8_STAGE(PG8_SA(0, 0), cA, voffA); PG8_STAGE(PG8_SA(0, 1), cA + hstepA, voffA);
;     if (wr == 1) PG8_BAR;
;     PG8_WAIT_V(2); PG8_BAR;
;     PG8_STAGE(PG8_SB(1, 0), cB + kstep, voffB); PG8_STAGE(PG8_SA(1, 0), cA + kstep, voffA); PG8_STAGE(PG8_SB(1, 1), cB + hstepB + kstep, voffB);
;     PG8_WAIT_V(6); PG8_BAR;
.LBB0_812:
	s_waitcnt vmcnt(0)
	v_lshrrev_b32_e32 v14, 4, v0
	v_and_b32_e32 v165, 15, v0
	v_and_b32_e32 v14, 3, v14
	v_lshlrev_b32_e32 v15, 4, v14
	v_lshlrev_b32_e32 v17, 2, v165
	v_lshl_or_b32 v16, v165, 6, v15
	s_lshl_b32 s19, s0, 13
	v_and_b32_e32 v18, 32, v17
	s_mov_b64 s[26:27], 0x80
	s_and_b32 s1, s1, 3
	v_bitop3_b32 v16, v16, s19, v18 bitop3:0xde
	v_lshlrev_b32_e32 v18, 6, v0
	s_movk_i32 s19, 0x3c0
	s_add_i32 m0, s11, 0x18000
	v_lshl_add_u64 v[6:7], v[6:7], 0, s[26:27]
	s_lshl_b32 s22, s0, 6
	v_and_or_b32 v15, v18, s19, v15
	s_lshl_b32 s19, s1, 12
	s_waitcnt vmcnt(2)
	s_barrier
	global_load_lds_dwordx4 v[6:7], off
	v_lshl_add_u64 v[4:5], v[4:5], 0, s[26:27]
	s_add_i32 m0, s11, 0x1a000
	s_add_i32 s84, s11, 0x8000
	s_add_i32 s85, s11, 0xa000
	global_load_lds_dwordx4 v[4:5], off
	v_lshl_add_u64 v[2:3], v[2:3], 0, s[26:27]
	s_mov_b32 m0, s84
	s_add_u32 s20, s6, 0x40080
	global_load_lds_dwordx4 v[2:3], off
	v_lshl_add_u64 v[2:3], v[8:9], 0, s[26:27]
	s_mov_b32 m0, s85
	s_addc_u32 s21, s7, 0
	global_load_lds_dwordx4 v[2:3], off
	s_add_i32 m0, s11, 0x1c000
	v_lshl_add_u64 v[2:3], s[20:21], 0, v[156:157]
	global_load_lds_dwordx4 v[2:3], off
	v_lshl_add_u64 v[2:3], s[20:21], 0, v[160:161]
	s_add_i32 m0, s11, 0x1e000
	s_cmpk_lt_u32 s8, 0x100
	global_load_lds_dwordx4 v[2:3], off
	s_cselect_b64 s[28:29], -1, 0
	s_cmp_eq_u32 s1, 0
	s_cselect_b64 s[20:21], -1, 0
	v_cmp_gt_u32_e32 vcc, 2, v14
	s_and_b64 s[20:21], s[20:21], vcc
	v_writelane_b32 v252, s20, 38
	s_lshl_b32 s8, s1, 6
	s_or_b32 s8, s8, 0xfffff400
	v_writelane_b32 v252, s21, 39
	v_writelane_b32 v252, s8, 40
	s_lshl_b32 s0, s0, 8
	v_writelane_b32 v252, s22, 41
	s_add_i32 s8, s22, 0x80
	s_add_i32 s0, s0, 0
	v_writelane_b32 v252, s8, 42
	s_add_i32 s0, s0, 0x20800
	v_add_u32_e32 v209, s0, v17
	s_lshl_b32 s0, s1, 7
	v_readlane_b32 s20, v252, 32
	v_readlane_b32 s21, v252, 33
	s_add_u32 s90, s20, s0
	s_addc_u32 s91, s21, 0
	s_lshl_b32 s0, s1, 8
	v_lshlrev_b32_e32 v164, 3, v14
	s_add_u32 s0, s50, s0
	v_lshl_or_b32 v166, s1, 5, v164
	s_addc_u32 s1, s51, 0
	s_add_u32 s38, s0, 0x4400000
	s_addc_u32 s39, s1, 0
	s_add_u32 s0, s0, 0x4100000
	s_addc_u32 s1, s1, 0
	v_lshlrev_b32_e32 v2, 2, v0
	v_writelane_b32 v252, s0, 43
	v_and_b32_e32 v2, 32, v2
	v_bitop3_b32 v196, s19, v15, v2 bitop3:0xf6
	v_writelane_b32 v252, s1, 44
	s_add_u32 s0, s68, 0xe900200
	s_addc_u32 s1, s69, 0
	v_lshlrev_b32_e32 v2, 8, v0
	v_writelane_b32 v252, s0, 45
	v_and_b32_e32 v2, 0x18000, v2
	v_lshlrev_b32_e32 v3, 11, v12
	v_writelane_b32 v252, s1, 46
	s_add_u32 s0, s50, 0x4440000
	v_or3_b32 v2, v10, v2, v3
	v_lshlrev_b32_e32 v162, 5, v14
	s_addc_u32 s1, s51, 0
	v_add_u32_e32 v172, v2, v11
	v_lshlrev_b32_e32 v2, 4, v13
	v_lshl_add_u64 v[168:169], s[96:97], 0, v[162:163]
	v_lshlrev_b32_e32 v162, 2, v166
	v_writelane_b32 v252, s0, 47
	v_and_b32_e32 v2, 0x38000, v2
	s_waitcnt vmcnt(6)
	v_or3_b32 v2, v10, v2, v3
	v_writelane_b32 v252, s1, 48
	v_lshl_add_u64 v[170:171], s[0:1], 0, v[162:163]
	s_add_u32 s0, s50, 0x4180000
	v_or_b32_e32 v167, s22, v165
	s_addc_u32 s1, s51, 0
	v_add_u32_e32 v174, v2, v11
	s_add_i32 s19, 0, 0x10000
	s_add_i32 s22, 0, 0x14000
	s_mov_b32 s52, 0xff000000
	v_mbcnt_lo_u32_b32 v2, -1, 0
	v_or_b32_e32 v197, 16, v167
	v_or_b32_e32 v200, 32, v167
	v_or_b32_e32 v201, 48, v167
	v_add_u32_e32 v202, 0x80, v167
	v_add_u32_e32 v203, 0x90, v167
	v_add_u32_e32 v204, 0xa0, v167
	v_add_u32_e32 v205, 0xb0, v167
	v_or_b32_e32 v206, 16, v165
	v_or_b32_e32 v207, 32, v165
	v_or_b32_e32 v208, 48, v165
	v_writelane_b32 v252, s0, 49
	v_mov_b32_e32 v173, v163
	v_mov_b32_e32 v175, v163
	v_mov_b64_e32 v[176:177], 0x6db
	v_mov_b64_e32 v[178:179], 0x6da
	v_add_u32_e32 v210, s19, v196
	v_add_u32_e32 v211, s22, v196
	v_add_u32_e32 v212, 0, v16
	v_mov_b32_e32 v213, 0x358637bd
	s_mov_b32 s53, -1
	s_mov_b32 s23, 0x42200000
	s_movk_i32 s34, 0xf000
	v_mbcnt_hi_u32_b32 v214, -1, v2
	v_mov_b32_e32 v215, 0x3db504f3
	s_mov_b32 s8, 0
	s_mov_b32 s35, 0
	s_barrier
	v_writelane_b32 v252, s1, 50
	s_mov_b32 s98, 0
	s_branch .LBB0_815
.LBB0_813:
	s_mov_b64 s[0:1], 0
	s_cmp_lg_u32 s10, 26
	s_cselect_b32 s98, 2, 0

; #define PG8_STAGE(bufoff, gbase, voff) do { _Pragma("unroll") for (int _i = 0; _i < 2; ++_i) \
;         __builtin_amdgcn_global_load_lds((const unsigned*)((const char*)(gbase) + (voff)[_i]), (LAS unsigned*)(lds + (bufoff) + ldsw + _i * 8192), 16, 0, 0); } while (0)
; #define PG8_LDA(dst, b, h) do { _Pragma("unroll") for (int m = 0; m < 4; ++m) _Pragma("unroll") for (int k = 0; k < 2; ++k) dst[m][k] = *(const LAS bf16x8*)(lds + PG8_SA(b, h) + aoff + m * 2048 + k * 1024); } while (0)
; #define PG8_LDB(dst, b, h) do { _Pragma("unroll") for (int n = 0; n < 2; ++n) _Pragma("unroll") for (int k = 0; k < 2; ++k) dst[n][k] = *(const LAS bf16x8*)(lds + PG8_SB(b, h) + boff + n * 2048 + k * 1024); } while (0)
; #define PG8_MMA(ai, bj, At, Bt) do { __builtin_amdgcn_s_setprio(1); _Pragma("unroll") for (int m = 0; m < 4; ++m) _Pragma("unroll") for (int n = 0; n < 2; ++n) _Pragma("unroll") for (int k = 0; k < 2; ++k) \
;         acc[ai][bj][m][n] = __builtin_amdgcn_mfma_f32_16x16x32_bf16(Bt[n][k], At[m][k], acc[ai][bj][m][n], 0, 0, 0); __builtin_amdgcn_s_setprio(0); } while (0)
; #define PG8_WAIT_V(n) asm volatile("s_waitcnt vmcnt(" #n ")" ::: "memory")
; #define PG8_WAIT_L(n) asm volatile("s_waitcnt lgkmcnt(" #n ")" ::: "memory")
; #define PG8_BAR __builtin_amdgcn_s_barrier()
; #define PG8_SCHED __builtin_amdgcn_sched_barrier(0)
; template <class Epi>
; __device__ __forceinline__ void gemm_phase(LAS unsigned char* lds, const Gemm g, const Sched& S, const Epi& E) {
;     ...
;             PG8_LDB(B0, 0, 0); PG8_LDB(B1, 0, 1); PG8_SCHED; PG8_LDA(At, 0, 0); PG8_STAGE(PG8_SA(1, 1), a1 + hstepA, voffA);
;             PG8_WAIT_V(8); PG8_WAIT_L(0); PG8_BAR; PG8_MMA(0, 0, At, B0); PG8_MMA(0, 1, At, B1); PG8_BAR; PG8_SCHED;
.LBB0_822:
	ds_read_b128 v[130:133], v210
	ds_read_b128 v[134:137], v210 offset:1024
	ds_read_b128 v[138:141], v210 offset:2048
	ds_read_b128 v[142:145], v210 offset:3072
	ds_read_b128 v[146:149], v211
	ds_read_b128 v[150:153], v211 offset:1024
	ds_read_b128 v[180:183], v211 offset:2048
	ds_read_b128 v[184:187], v211 offset:3072
	s_add_u32 s6, s4, 0xfffc0080
	s_addc_u32 s7, s5, -1
	s_cmp_eq_u32 s77, 12
	s_cselect_b32 s21, s25, s7
	s_cselect_b32 s20, s55, s6
	s_cselect_b32 s7, s72, s75
	s_cselect_b32 s6, s73, s74
	v_lshl_add_u64 v[240:241], s[4:5], 0, v[172:173]
	s_add_i32 m0, s11, 0xc000
	ds_read_b128 v[188:191], v212
	ds_read_b128 v[192:195], v212 offset:1024
	ds_read_b128 v[216:219], v212 offset:2048
	ds_read_b128 v[220:223], v212 offset:3072
	ds_read_b128 v[224:227], v212 offset:4096
	ds_read_b128 v[228:231], v212 offset:5120
	ds_read_b128 v[232:235], v212 offset:6144
	ds_read_b128 v[236:239], v212 offset:7168
	global_load_lds_dwordx4 v[240:241], off
	v_lshl_add_u64 v[240:241], s[4:5], 0, v[174:175]
	s_add_i32 m0, s11, 0xe000
	s_nop 0
	global_load_lds_dwordx4 v[240:241], off
	s_cmp_eq_u32 s98, 0
	s_cbranch_scc1 .Lrx_p3_0_n
	s_sub_u32 s98, s98, 1
	s_waitcnt vmcnt(24)
	s_branch .Lrx_p3_0_j

; #define PG8_STAGE(bufoff, gbase, voff) do { _Pragma("unroll") for (int _i = 0; _i < 2; ++_i) \
;         __builtin_amdgcn_global_load_lds((const unsigned*)((const char*)(gbase) + (voff)[_i]), (LAS unsigned*)(lds + (bufoff) + ldsw + _i * 8192), 16, 0, 0); } while (0)
; #define PG8_LDA(dst, b, h) do { _Pragma("unroll") for (int m = 0; m < 4; ++m) _Pragma("unroll") for (int k = 0; k < 2; ++k) dst[m][k] = *(const LAS bf16x8*)(lds + PG8_SA(b, h) + aoff + m * 2048 + k * 1024); } while (0)
; #define PG8_MMA(ai, bj, At, Bt) do { __builtin_amdgcn_s_setprio(1); _Pragma("unroll") for (int m = 0; m < 4; ++m) _Pragma("unroll") for (int n = 0; n < 2; ++n) _Pragma("unroll") for (int k = 0; k < 2; ++k) \
;         acc[ai][bj][m][n] = __builtin_amdgcn_mfma_f32_16x16x32_bf16(Bt[n][k], At[m][k], acc[ai][bj][m][n], 0, 0, 0); __builtin_amdgcn_s_setprio(0); } while (0)
; #define PG8_WAIT_V(n) asm volatile("s_waitcnt vmcnt(" #n ")" ::: "memory")
; #define PG8_WAIT_L(n) asm volatile("s_waitcnt lgkmcnt(" #n ")" ::: "memory")
; #define PG8_BAR __builtin_amdgcn_s_barrier()
; #define PG8_SCHED __builtin_amdgcn_sched_barrier(0)
; template <class Epi>
; __device__ __forceinline__ void gemm_phase(LAS unsigned char* lds, const Gemm g, const Sched& S, const Epi& E) {
;     ...
;             PG8_WAIT_V(8); PG8_WAIT_L(0); PG8_BAR; PG8_MMA(0, 0, At, B0); PG8_MMA(0, 1, At, B1); PG8_BAR; PG8_SCHED;
;             PG8_LDA(At, 0, 1); PG8_STAGE(PG8_SB(0, 0), b2, voffB); PG8_STAGE(PG8_SB(0, 1), b2 + hstepB, voffB); PG8_STAGE(PG8_SA(0, 0), a2, voffA);
;             PG8_WAIT_V(8); PG8_WAIT_L(0); PG8_BAR; PG8_MMA(1, 0, At, B0); PG8_MMA(1, 1, At, B1); PG8_BAR; PG8_SCHED;
.Lrx_p3_0_j:
	s_waitcnt lgkmcnt(0)
	s_cmp_eq_u32 s77, -2
	s_cbranch_scc1 .Lcz_p3_0
	s_barrier
	s_setprio 1
	s_waitcnt lgkmcnt(0)
	v_mfma_f32_16x16x32_bf16 v[126:129], v[130:133], v[188:191], v[126:129]
	v_mfma_f32_16x16x32_bf16 v[122:125], v[138:141], v[188:191], v[122:125]
	v_mfma_f32_16x16x32_bf16 v[110:113], v[130:133], v[216:219], v[110:113]
	v_mfma_f32_16x16x32_bf16 v[106:109], v[138:141], v[216:219], v[106:109]
	v_mfma_f32_16x16x32_bf16 v[94:97], v[130:133], v[224:227], v[94:97]
	v_mfma_f32_16x16x32_bf16 v[90:93], v[138:141], v[224:227], v[90:93]
	v_mfma_f32_16x16x32_bf16 v[78:81], v[130:133], v[232:235], v[78:81]
	v_mfma_f32_16x16x32_bf16 v[74:77], v[138:141], v[232:235], v[74:77]
	v_mfma_f32_16x16x32_bf16 v[126:129], v[134:137], v[192:195], v[126:129]
	v_mfma_f32_16x16x32_bf16 v[122:125], v[142:145], v[192:195], v[122:125]
	v_mfma_f32_16x16x32_bf16 v[110:113], v[134:137], v[220:223], v[110:113]
	v_mfma_f32_16x16x32_bf16 v[106:109], v[142:145], v[220:223], v[106:109]
	v_mfma_f32_16x16x32_bf16 v[94:97], v[134:137], v[228:231], v[94:97]
	v_mfma_f32_16x16x32_bf16 v[90:93], v[142:145], v[228:231], v[90:93]
	v_mfma_f32_16x16x32_bf16 v[78:81], v[134:137], v[236:239], v[78:81]
	v_mfma_f32_16x16x32_bf16 v[74:77], v[142:145], v[236:239], v[74:77]
	s_setprio 0
	s_setprio 1
	v_mfma_f32_16x16x32_bf16 v[118:121], v[146:149], v[188:191], v[118:121]
	v_mfma_f32_16x16x32_bf16 v[114:117], v[180:183], v[188:191], v[114:117]
	v_mfma_f32_16x16x32_bf16 v[102:105], v[146:149], v[216:219], v[102:105]
	v_mfma_f32_16x16x32_bf16 v[98:101], v[180:183], v[216:219], v[98:101]
	v_mfma_f32_16x16x32_bf16 v[86:89], v[146:149], v[224:227], v[86:89]
	v_mfma_f32_16x16x32_bf16 v[82:85], v[180:183], v[224:227], v[82:85]
	v_mfma_f32_16x16x32_bf16 v[70:73], v[146:149], v[232:235], v[70:73]
	v_mfma_f32_16x16x32_bf16 v[66:69], v[180:183], v[232:235], v[66:69]
	v_mfma_f32_16x16x32_bf16 v[118:121], v[150:153], v[192:195], v[118:121]
	v_mfma_f32_16x16x32_bf16 v[114:117], v[184:187], v[192:195], v[114:117]
	v_mfma_f32_16x16x32_bf16 v[102:105], v[150:153], v[220:223], v[102:105]
	v_mfma_f32_16x16x32_bf16 v[98:101], v[184:187], v[220:223], v[98:101]
	v_mfma_f32_16x16x32_bf16 v[86:89], v[150:153], v[228:231], v[86:89]
	v_mfma_f32_16x16x32_bf16 v[82:85], v[184:187], v[228:231], v[82:85]
	v_mfma_f32_16x16x32_bf16 v[70:73], v[150:153], v[236:239], v[70:73]
	v_mfma_f32_16x16x32_bf16 v[66:69], v[184:187], v[236:239], v[66:69]
.Lcz_p3_0_j:
	s_setprio 0
	s_barrier
	s_add_i32 s82, s19, s78
	v_lshl_add_u64 v[240:241], s[6:7], 0, v[156:157]
	s_mov_b32 m0, s82
	ds_read_b128 v[188:191], v212 offset:16384
	ds_read_b128 v[192:195], v212 offset:17408
	ds_read_b128 v[216:219], v212 offset:18432
	ds_read_b128 v[220:223], v212 offset:19456
	ds_read_b128 v[224:227], v212 offset:20480
	ds_read_b128 v[228:231], v212 offset:21504
	ds_read_b128 v[232:235], v212 offset:22528
	ds_read_b128 v[236:239], v212 offset:23552
	global_load_lds_dwordx4 v[240:241], off
	s_add_i32 m0, s82, 0x2000
	s_add_u32 s82, s6, 0x40000
	v_lshl_add_u64 v[242:243], s[6:7], 0, v[160:161]
	s_addc_u32 s83, s7, 0
	s_add_i32 s86, s22, s78
	global_load_lds_dwordx4 v[242:243], off
	v_lshl_add_u64 v[244:245], s[82:83], 0, v[156:157]
	s_mov_b32 m0, s86
	v_lshl_add_u64 v[246:247], s[20:21], 0, v[158:159]
	global_load_lds_dwordx4 v[244:245], off
	v_lshl_add_u64 v[244:245], s[82:83], 0, v[160:161]
	s_add_i32 m0, s86, 0x2000
	s_nop 0
	global_load_lds_dwordx4 v[244:245], off
	v_lshl_add_u64 v[244:245], s[20:21], 0, v[154:155]
	s_mov_b32 m0, s11
	s_nop 0
	global_load_lds_dwordx4 v[244:245], off
	s_mov_b32 m0, s31
	s_nop 0
	global_load_lds_dwordx4 v[246:247], off
	s_cmp_eq_u32 s98, 0
	s_cbranch_scc1 .Lrx_p3_1_n
	s_sub_u32 s98, s98, 1
	s_waitcnt vmcnt(24)
	s_branch .Lrx_p3_1_j

; #define PG8_STAGE(bufoff, gbase, voff) do { _Pragma("unroll") for (int _i = 0; _i < 2; ++_i) \
;         __builtin_amdgcn_global_load_lds((const unsigned*)((const char*)(gbase) + (voff)[_i]), (LAS unsigned*)(lds + (bufoff) + ldsw + _i * 8192), 16, 0, 0); } while (0)
; #define PG8_LDA(dst, b, h) do { _Pragma("unroll") for (int m = 0; m < 4; ++m) _Pragma("unroll") for (int k = 0; k < 2; ++k) dst[m][k] = *(const LAS bf16x8*)(lds + PG8_SA(b, h) + aoff + m * 2048 + k * 1024); } while (0)
; #define PG8_MMA(ai, bj, At, Bt) do { __builtin_amdgcn_s_setprio(1); _Pragma("unroll") for (int m = 0; m < 4; ++m) _Pragma("unroll") for (int n = 0; n < 2; ++n) _Pragma("unroll") for (int k = 0; k < 2; ++k) \
;         acc[ai][bj][m][n] = __builtin_amdgcn_mfma_f32_16x16x32_bf16(Bt[n][k], At[m][k], acc[ai][bj][m][n], 0, 0, 0); __builtin_amdgcn_s_setprio(0); } while (0)
; #define PG8_WAIT_V(n) asm volatile("s_waitcnt vmcnt(" #n ")" ::: "memory")
; #define PG8_WAIT_L(n) asm volatile("s_waitcnt lgkmcnt(" #n ")" ::: "memory")
; #define PG8_BAR __builtin_amdgcn_s_barrier()
; #define PG8_SCHED __builtin_amdgcn_sched_barrier(0)
; template <class Epi>
; __device__ __forceinline__ void gemm_phase(LAS unsigned char* lds, const Gemm g, const Sched& S, const Epi& E) {
;     ...
;             PG8_WAIT_V(8); PG8_WAIT_L(0); PG8_BAR; PG8_MMA(0, 0, At, B0); PG8_MMA(0, 1, At, B1); PG8_BAR; PG8_SCHED;
;             PG8_LDA(At, 0, 1); PG8_STAGE(PG8_SB(0, 0), b2, voffB); PG8_STAGE(PG8_SB(0, 1), b2 + hstepB, voffB); PG8_STAGE(PG8_SA(0, 0), a2, voffA);
;             PG8_WAIT_V(8); PG8_WAIT_L(0); PG8_BAR; PG8_MMA(1, 0, At, B0); PG8_MMA(1, 1, At, B1); PG8_BAR; PG8_SCHED;
.Lrx_p3_1_j:
	s_waitcnt lgkmcnt(0)
	s_cmp_eq_u32 s77, -2
	s_cbranch_scc1 .Lcz_p3_1
	s_barrier
	s_setprio 1
	s_waitcnt lgkmcnt(0)
	v_mfma_f32_16x16x32_bf16 v[62:65], v[130:133], v[188:191], v[62:65]
	v_mfma_f32_16x16x32_bf16 v[58:61], v[138:141], v[188:191], v[58:61]
	v_mfma_f32_16x16x32_bf16 v[46:49], v[130:133], v[216:219], v[46:49]
	v_mfma_f32_16x16x32_bf16 v[42:45], v[138:141], v[216:219], v[42:45]
	v_mfma_f32_16x16x32_bf16 v[30:33], v[130:133], v[224:227], v[30:33]
	v_mfma_f32_16x16x32_bf16 v[26:29], v[138:141], v[224:227], v[26:29]
	v_mfma_f32_16x16x32_bf16 v[14:17], v[130:133], v[232:235], v[14:17]
	v_mfma_f32_16x16x32_bf16 v[10:13], v[138:141], v[232:235], v[10:13]
	v_mfma_f32_16x16x32_bf16 v[62:65], v[134:137], v[192:195], v[62:65]
	v_mfma_f32_16x16x32_bf16 v[58:61], v[142:145], v[192:195], v[58:61]
	v_mfma_f32_16x16x32_bf16 v[46:49], v[134:137], v[220:223], v[46:49]
	v_mfma_f32_16x16x32_bf16 v[42:45], v[142:145], v[220:223], v[42:45]
	v_mfma_f32_16x16x32_bf16 v[30:33], v[134:137], v[228:231], v[30:33]
	v_mfma_f32_16x16x32_bf16 v[26:29], v[142:145], v[228:231], v[26:29]
	v_mfma_f32_16x16x32_bf16 v[14:17], v[134:137], v[236:239], v[14:17]
	v_mfma_f32_16x16x32_bf16 v[10:13], v[142:145], v[236:239], v[10:13]
	s_setprio 0
	s_setprio 1
	v_mfma_f32_16x16x32_bf16 v[54:57], v[146:149], v[188:191], v[54:57]
	v_mfma_f32_16x16x32_bf16 v[50:53], v[180:183], v[188:191], v[50:53]
	v_mfma_f32_16x16x32_bf16 v[38:41], v[146:149], v[216:219], v[38:41]
	v_mfma_f32_16x16x32_bf16 v[34:37], v[180:183], v[216:219], v[34:37]
	v_mfma_f32_16x16x32_bf16 v[22:25], v[146:149], v[224:227], v[22:25]
	v_mfma_f32_16x16x32_bf16 v[18:21], v[180:183], v[224:227], v[18:21]
	v_mfma_f32_16x16x32_bf16 v[6:9], v[146:149], v[232:235], v[6:9]
	v_mfma_f32_16x16x32_bf16 v[2:5], v[180:183], v[232:235], v[2:5]
	v_mfma_f32_16x16x32_bf16 v[54:57], v[150:153], v[192:195], v[54:57]
	v_mfma_f32_16x16x32_bf16 v[50:53], v[184:187], v[192:195], v[50:53]
	v_mfma_f32_16x16x32_bf16 v[38:41], v[150:153], v[220:223], v[38:41]
	v_mfma_f32_16x16x32_bf16 v[34:37], v[184:187], v[220:223], v[34:37]
	v_mfma_f32_16x16x32_bf16 v[22:25], v[150:153], v[228:231], v[22:25]
	v_mfma_f32_16x16x32_bf16 v[18:21], v[184:187], v[228:231], v[18:21]
	v_mfma_f32_16x16x32_bf16 v[6:9], v[150:153], v[236:239], v[6:9]
	v_mfma_f32_16x16x32_bf16 v[2:5], v[184:187], v[236:239], v[2:5]
